# mem_w_kv conversion assigned to the upper half of the wave range (phase-0 item balance)
# baseline (speedup 1.0000x reference)
; #define LAS __attribute__((address_space(3)))
; __device__ __forceinline__ void conv_matrix(const float* W, int K, int N, const float* gain, bf16_t* WT, int Kd, int mode, int row_off, LAS float* scr, int lane, int gw, int NGW) {
;     const int nblk = N / 32, items = nblk * (K / 64);
;     for (int it = gw; it < items; it += NGW) {
;         const int kb = it / nblk, nb = it % nblk, k0 = 64 * kb, n0 = 32 * nb;
;         float wv[32];
; #pragma unroll
;         for (int i = 0; i < 32; ++i) wv[i] = W[(size_t)(k0 + 2 * i + (lane >> 5)) * N + n0 + (lane & 31)];
.LBB0_136:
	s_sub_i32 s12, s8, s4
	s_add_i32 s12, s12, -1
	s_cmpk_gt_i32 s12, 0x3ff
	s_cbranch_scc1 .LBB0_141
	v_readlane_b32 s5, v254, 20
	s_mov_b64 s[16:17], 0xd800000
	v_lshl_add_u64 v[4:5], v[4:5], 0, s[16:17]
	v_mov_b32_e32 v6, s5
	v_readlane_b32 s5, v254, 21
	s_lshl_b32 s9, s8, 5
	v_mov_b32_e32 v7, s5
	ds_read_b64 v[8:9], v7
	ds_read_b64 v[6:7], v6
	s_lshl_b32 s5, s12, 5
	s_waitcnt lgkmcnt(0)
	v_lshl_add_u64 v[2:3], v[2:3], 2, v[8:9]
	v_cmp_ne_u64_e64 s[40:41], 0, v[6:7]
	s_branch .LBB0_139
